# S4 epilogue: copy-chunk draw atomic no longer waited mid-epilogue; result picked up at the end (vmcnt(4))
# speedup vs baseline: 1.0133x; 1.0108x over previous
.LBB0_1030:
	s_mov_b32 s98, 0
	s_cmp_lt_i32 s1, 10
	s_cselect_b64 s[0:1], -1, 0
	s_and_b64 s[0:1], s[80:81], s[0:1]
	v_mov_b32_e32 v74, 0x1550
	s_and_saveexec_b64 s[6:7], s[0:1]
	s_cbranch_execz .LBB0_1035
	v_mov_b32_e32 v74, s70
	ds_read_b32 v74, v74
	s_waitcnt lgkmcnt(0)
	v_cmp_ne_u32_e32 vcc, 0, v74
	v_mov_b32_e32 v74, 0x1550
	s_cbranch_vccnz .LBB0_1035
	s_mov_b64 s[2:3], exec
	s_mov_b32 s98, 1
	v_mbcnt_lo_u32_b32 v74, s2, 0
	v_mbcnt_hi_u32_b32 v74, s3, v74
	v_cmp_eq_u32_e32 vcc, 0, v74
	s_and_saveexec_b64 s[4:5], vcc
	s_cbranch_execz .LBB0_1034
	s_bcnt1_i32_b64 s0, s[2:3]
	v_mov_b32_e32 v247, s0
	global_atomic_add v247, v185, v247, s[34:35] sc0

.LBB0_1035:
	s_or_b64 exec, exec, s[6:7]
	v_mov_b32_e32 v76, v107
	v_mov_b32_e32 v77, v108
	v_mov_b32_e32 v107, v109
	v_pk_add_f32 v[76:77], v[76:77], v[106:107]
	s_nop 0
	v_add_f32_e32 v75, v76, v77
	ds_bpermute_b32 v76, v199, v75
	s_waitcnt lgkmcnt(0)
	v_add_f32_e32 v75, v75, v76
	ds_bpermute_b32 v76, v174, v75
	s_waitcnt lgkmcnt(0)
	v_add_f32_e32 v75, v75, v76
	v_fmamk_f32 v75, v75, 0x3a800000, v222
	v_rsq_f32_e32 v76, v75
	s_nop 0
	v_pk_mul_f32 v[62:63], v[62:63], v[76:77] op_sel_hi:[1,0]
	v_pk_mul_f32 v[58:59], v[58:59], v[76:77] op_sel_hi:[1,0]
	v_pk_mul_f32 v[64:65], v[64:65], v[76:77] op_sel_hi:[1,0]
	v_pk_mul_f32 v[60:61], v[60:61], v[76:77] op_sel_hi:[1,0]
	v_pk_mul_f32 v[54:55], v[54:55], v[76:77] op_sel_hi:[1,0]
	v_mul_f32_e32 v75, 0xbfb8aa3b, v62
	v_mul_f32_e32 v77, 0xbfb8aa3b, v63
	v_exp_f32_e32 v75, v75
	v_exp_f32_e32 v77, v77
	v_mul_f32_e32 v78, 0xbfb8aa3b, v64
	v_mul_f32_e32 v79, 0xbfb8aa3b, v65
	v_add_f32_e32 v75, 1.0, v75
	v_add_f32_e32 v77, 1.0, v77
	v_exp_f32_e32 v80, v78
	v_exp_f32_e32 v81, v79
	v_rcp_f32_e32 v78, v75
	v_rcp_f32_e32 v79, v77
	v_add_f32_e32 v75, 1.0, v80
	v_add_f32_e32 v77, 1.0, v81
	v_pk_mul_f32 v[56:57], v[56:57], v[76:77] op_sel_hi:[1,0]
	v_pk_mul_f32 v[62:63], v[62:63], v[78:79]
	v_pk_mul_f32 v[50:51], v[50:51], v[76:77] op_sel_hi:[1,0]
	v_pk_mul_f32 v[58:59], v[58:59], v[62:63]
	v_mul_f32_e32 v62, 0xbfb8aa3b, v54
	v_mul_f32_e32 v63, 0xbfb8aa3b, v55
	v_exp_f32_e32 v62, v62
	v_exp_f32_e32 v63, v63
	v_pk_mul_f32 v[52:53], v[52:53], v[76:77] op_sel_hi:[1,0]
	v_rcp_f32_e32 v80, v75
	v_add_f32_e32 v62, 1.0, v62
	v_add_f32_e32 v63, 1.0, v63
	v_rcp_f32_e32 v62, v62
	v_rcp_f32_e32 v63, v63
	v_rcp_f32_e32 v81, v77
	v_pk_mul_f32 v[54:55], v[54:55], v[62:63]
	v_mul_f32_e32 v62, 0xbfb8aa3b, v56
	v_mul_f32_e32 v63, 0xbfb8aa3b, v57
	v_exp_f32_e32 v62, v62
	v_exp_f32_e32 v63, v63
	v_pk_mul_f32 v[50:51], v[50:51], v[54:55]
	v_pk_mul_f32 v[64:65], v[64:65], v[80:81]
	v_add_f32_e32 v54, 1.0, v62
	v_add_f32_e32 v55, 1.0, v63
	v_mov_b32_e32 v62, v87
	v_mov_b32_e32 v63, v88
	v_mov_b32_e32 v87, v89
	v_pk_add_f32 v[62:63], v[62:63], v[86:87]
	v_rcp_f32_e32 v54, v54
	v_add_f32_e32 v62, v62, v63
	v_rcp_f32_e32 v55, v55
	ds_bpermute_b32 v63, v199, v62
	v_pk_mul_f32 v[60:61], v[60:61], v[64:65]
	v_pk_mul_f32 v[54:55], v[56:57], v[54:55]
	s_nop 0
	v_pk_mul_f32 v[56:57], v[52:53], v[54:55]
	v_cvt_pk_bf16_f32 v52, v58, v59
	s_waitcnt lgkmcnt(0)
	v_add_f32_e32 v58, v62, v63
	ds_bpermute_b32 v59, v174, v58
	v_cvt_pk_bf16_f32 v55, v56, v57
	v_cvt_pk_bf16_f32 v54, v50, v51
	v_mov_b64_e32 v[50:51], s[26:27]
	v_cvt_pk_bf16_f32 v53, v60, v61
	s_waitcnt lgkmcnt(0)
	v_add_f32_e32 v56, v58, v59
	v_fmamk_f32 v56, v56, 0x3a800000, v222
	v_rsq_f32_e32 v56, v56
	v_mad_i64_i32 v[58:59], s[0:1], v202, s68, v[50:51]
	v_lshl_add_u64 v[58:59], v[58:59], 0, v[130:131]
	v_pk_mul_f32 v[46:47], v[46:47], v[56:57] op_sel_hi:[1,0]
	global_store_dwordx4 v[58:59], v[52:55], off
	v_mul_f32_e32 v57, 0xbfb8aa3b, v46
	v_exp_f32_e32 v57, v57
	v_mul_f32_e32 v52, 0xbfb8aa3b, v47
	v_exp_f32_e32 v53, v52
	v_pk_mul_f32 v[48:49], v[48:49], v[56:57] op_sel_hi:[1,0]
	s_nop 0
	v_mul_f32_e32 v54, 0xbfb8aa3b, v48
	v_mul_f32_e32 v55, 0xbfb8aa3b, v49
	v_exp_f32_e32 v54, v54
	v_exp_f32_e32 v55, v55
	v_add_f32_e32 v52, 1.0, v57
	v_add_f32_e32 v53, 1.0, v53
	v_rcp_f32_e32 v52, v52
	v_rcp_f32_e32 v53, v53
	v_add_f32_e32 v54, 1.0, v54
	v_add_f32_e32 v55, 1.0, v55
	v_rcp_f32_e32 v54, v54
	v_rcp_f32_e32 v55, v55
	v_pk_mul_f32 v[38:39], v[38:39], v[56:57] op_sel_hi:[1,0]
	v_pk_mul_f32 v[46:47], v[46:47], v[52:53]
	v_pk_mul_f32 v[40:41], v[40:41], v[56:57] op_sel_hi:[1,0]
	v_pk_mul_f32 v[38:39], v[38:39], v[46:47]
	v_pk_mul_f32 v[46:47], v[48:49], v[54:55]
	v_pk_mul_f32 v[42:43], v[42:43], v[56:57] op_sel_hi:[1,0]
	v_pk_mul_f32 v[40:41], v[40:41], v[46:47]
	v_mul_f32_e32 v48, 0xbfb8aa3b, v42
	v_mul_f32_e32 v46, 0xbfb8aa3b, v43
	v_exp_f32_e32 v48, v48
	v_exp_f32_e32 v47, v46
	v_pk_mul_f32 v[44:45], v[44:45], v[56:57] op_sel_hi:[1,0]
	v_pk_mul_f32 v[34:35], v[34:35], v[56:57] op_sel_hi:[1,0]
	v_add_f32_e32 v46, 1.0, v48
	v_add_f32_e32 v47, 1.0, v47
	v_mul_f32_e32 v48, 0xbfb8aa3b, v44
	v_mul_f32_e32 v49, 0xbfb8aa3b, v45
	v_rcp_f32_e32 v46, v46
	v_rcp_f32_e32 v47, v47
	v_exp_f32_e32 v48, v48
	v_exp_f32_e32 v49, v49
	v_pk_mul_f32 v[42:43], v[42:43], v[46:47]
	v_add_f32_e32 v46, 1.0, v48
	v_add_f32_e32 v47, 1.0, v49
	v_mov_b32_e32 v48, v71
	v_mov_b32_e32 v49, v72
	v_mov_b32_e32 v71, v73
	v_pk_add_f32 v[48:49], v[48:49], v[70:71]
	v_rcp_f32_e32 v46, v46
	v_add_f32_e32 v48, v48, v49
	ds_bpermute_b32 v49, v199, v48
	v_rcp_f32_e32 v47, v47
	v_pk_mul_f32 v[42:43], v[34:35], v[42:43]
	v_pk_mul_f32 v[34:35], v[36:37], v[56:57] op_sel_hi:[1,0]
	v_pk_mul_f32 v[36:37], v[44:45], v[46:47]
	s_waitcnt lgkmcnt(0)
	v_add_f32_e32 v46, v48, v49
	ds_bpermute_b32 v47, v174, v46
	v_pk_mul_f32 v[44:45], v[34:35], v[36:37]
	v_cvt_pk_bf16_f32 v34, v38, v39
	v_cvt_pk_bf16_f32 v35, v40, v41
	v_mad_i64_i32 v[40:41], s[0:1], v200, s68, v[50:51]
	s_waitcnt lgkmcnt(0)
	v_add_f32_e32 v38, v46, v47
	v_fmamk_f32 v38, v38, 0x3a800000, v222
	v_rsq_f32_e32 v38, v38
	v_cvt_pk_bf16_f32 v36, v42, v43
	v_cvt_pk_bf16_f32 v37, v44, v45
	v_lshl_add_u64 v[40:41], v[40:41], 0, v[130:131]
	v_pk_mul_f32 v[30:31], v[30:31], v[38:39] op_sel_hi:[1,0]
	global_store_dwordx4 v[40:41], v[34:37], off
	v_mul_f32_e32 v39, 0xbfb8aa3b, v30
	v_exp_f32_e32 v39, v39
	v_mul_f32_e32 v34, 0xbfb8aa3b, v31
	v_exp_f32_e32 v35, v34
	v_pk_mul_f32 v[32:33], v[32:33], v[38:39] op_sel_hi:[1,0]
	s_nop 0
	v_mul_f32_e32 v36, 0xbfb8aa3b, v32
	v_mul_f32_e32 v37, 0xbfb8aa3b, v33
	v_exp_f32_e32 v36, v36
	v_exp_f32_e32 v37, v37
	v_add_f32_e32 v34, 1.0, v39
	v_add_f32_e32 v35, 1.0, v35
	v_rcp_f32_e32 v34, v34
	v_rcp_f32_e32 v35, v35
	v_add_f32_e32 v36, 1.0, v36
	v_add_f32_e32 v37, 1.0, v37
	v_rcp_f32_e32 v36, v36
	v_rcp_f32_e32 v37, v37
	v_pk_mul_f32 v[22:23], v[22:23], v[38:39] op_sel_hi:[1,0]
	v_pk_mul_f32 v[30:31], v[30:31], v[34:35]
	v_pk_mul_f32 v[24:25], v[24:25], v[38:39] op_sel_hi:[1,0]
	v_pk_mul_f32 v[22:23], v[22:23], v[30:31]
	v_pk_mul_f32 v[30:31], v[32:33], v[36:37]
	v_pk_mul_f32 v[26:27], v[26:27], v[38:39] op_sel_hi:[1,0]
	v_pk_mul_f32 v[24:25], v[24:25], v[30:31]
	v_mul_f32_e32 v32, 0xbfb8aa3b, v26
	v_mul_f32_e32 v30, 0xbfb8aa3b, v27
	v_exp_f32_e32 v32, v32
	v_exp_f32_e32 v31, v30
	v_pk_mul_f32 v[28:29], v[28:29], v[38:39] op_sel_hi:[1,0]
	v_pk_mul_f32 v[18:19], v[18:19], v[38:39] op_sel_hi:[1,0]
	v_add_f32_e32 v30, 1.0, v32
	v_add_f32_e32 v31, 1.0, v31
	v_mul_f32_e32 v32, 0xbfb8aa3b, v28
	v_mul_f32_e32 v33, 0xbfb8aa3b, v29
	v_rcp_f32_e32 v30, v30
	v_rcp_f32_e32 v31, v31
	v_exp_f32_e32 v32, v32
	v_exp_f32_e32 v33, v33
	v_pk_mul_f32 v[26:27], v[26:27], v[30:31]
	v_add_f32_e32 v30, 1.0, v32
	v_add_f32_e32 v31, 1.0, v33
	v_mov_b32_e32 v32, v67
	v_mov_b32_e32 v33, v68
	v_mov_b32_e32 v67, v69
	v_pk_add_f32 v[32:33], v[32:33], v[66:67]
	v_rcp_f32_e32 v30, v30
	v_add_f32_e32 v32, v32, v33
	ds_bpermute_b32 v33, v199, v32
	v_rcp_f32_e32 v31, v31
	v_pk_mul_f32 v[26:27], v[18:19], v[26:27]
	v_pk_mul_f32 v[18:19], v[20:21], v[38:39] op_sel_hi:[1,0]
	v_pk_mul_f32 v[20:21], v[28:29], v[30:31]
	s_waitcnt lgkmcnt(0)
	v_add_f32_e32 v30, v32, v33
	ds_bpermute_b32 v31, v174, v30
	v_pk_mul_f32 v[28:29], v[18:19], v[20:21]
	v_cvt_pk_bf16_f32 v18, v22, v23
	v_cvt_pk_bf16_f32 v19, v24, v25
	v_mad_i64_i32 v[24:25], s[0:1], v198, s68, v[50:51]
	s_waitcnt lgkmcnt(0)
	v_add_f32_e32 v22, v30, v31
	v_fmamk_f32 v22, v22, 0x3a800000, v222
	v_rsq_f32_e32 v22, v22
	v_cvt_pk_bf16_f32 v20, v26, v27
	v_cvt_pk_bf16_f32 v21, v28, v29
	v_lshl_add_u64 v[24:25], v[24:25], 0, v[130:131]
	v_pk_mul_f32 v[14:15], v[14:15], v[22:23] op_sel_hi:[1,0]
	global_store_dwordx4 v[24:25], v[18:21], off
	v_mul_f32_e32 v23, 0xbfb8aa3b, v14
	v_exp_f32_e32 v23, v23
	v_mul_f32_e32 v18, 0xbfb8aa3b, v15
	v_exp_f32_e32 v19, v18
	v_pk_mul_f32 v[16:17], v[16:17], v[22:23] op_sel_hi:[1,0]
	s_nop 0
	v_mul_f32_e32 v20, 0xbfb8aa3b, v16
	v_mul_f32_e32 v21, 0xbfb8aa3b, v17
	v_exp_f32_e32 v20, v20
	v_exp_f32_e32 v21, v21
	v_add_f32_e32 v18, 1.0, v23
	v_add_f32_e32 v19, 1.0, v19
	v_rcp_f32_e32 v18, v18
	v_rcp_f32_e32 v19, v19
	v_add_f32_e32 v20, 1.0, v20
	v_add_f32_e32 v21, 1.0, v21
	v_rcp_f32_e32 v20, v20
	v_rcp_f32_e32 v21, v21
	v_pk_mul_f32 v[6:7], v[6:7], v[22:23] op_sel_hi:[1,0]
	v_pk_mul_f32 v[14:15], v[14:15], v[18:19]
	v_pk_mul_f32 v[10:11], v[10:11], v[22:23] op_sel_hi:[1,0]
	v_pk_mul_f32 v[6:7], v[6:7], v[14:15]
	v_pk_mul_f32 v[14:15], v[16:17], v[20:21]
	v_mul_f32_e32 v16, 0xbfb8aa3b, v10
	v_exp_f32_e32 v16, v16
	v_pk_mul_f32 v[8:9], v[8:9], v[22:23] op_sel_hi:[1,0]
	v_pk_mul_f32 v[12:13], v[12:13], v[22:23] op_sel_hi:[1,0]
	v_pk_mul_f32 v[8:9], v[8:9], v[14:15]
	v_mul_f32_e32 v14, 0xbfb8aa3b, v11
	v_exp_f32_e32 v15, v14
	v_add_f32_e32 v14, 1.0, v16
	v_mul_f32_e32 v16, 0xbfb8aa3b, v12
	v_mul_f32_e32 v17, 0xbfb8aa3b, v13
	v_exp_f32_e32 v16, v16
	v_exp_f32_e32 v17, v17
	v_add_f32_e32 v15, 1.0, v15
	v_rcp_f32_e32 v14, v14
	v_rcp_f32_e32 v15, v15
	v_add_f32_e32 v16, 1.0, v16
	v_add_f32_e32 v17, 1.0, v17
	v_rcp_f32_e32 v16, v16
	v_rcp_f32_e32 v17, v17
	v_pk_mul_f32 v[2:3], v[2:3], v[22:23] op_sel_hi:[1,0]
	v_pk_mul_f32 v[10:11], v[10:11], v[14:15]
	s_nop 0
	v_pk_mul_f32 v[10:11], v[2:3], v[10:11]
	v_pk_mul_f32 v[2:3], v[4:5], v[22:23] op_sel_hi:[1,0]
	v_pk_mul_f32 v[4:5], v[12:13], v[16:17]
	s_nop 0
	v_pk_mul_f32 v[12:13], v[2:3], v[4:5]
	v_cvt_pk_bf16_f32 v2, v6, v7
	v_mad_i64_i32 v[6:7], s[0:1], v196, s68, v[50:51]
	v_cvt_pk_bf16_f32 v3, v8, v9
	v_cvt_pk_bf16_f32 v4, v10, v11
	v_cvt_pk_bf16_f32 v5, v12, v13
	v_lshl_add_u64 v[6:7], v[6:7], 0, v[130:131]
	global_store_dwordx4 v[6:7], v[2:5], off
	s_and_saveexec_b64 s[6:7], s[80:81]
	s_cbranch_execz .LBB0_1037
	s_cmp_eq_u32 s98, 0
	s_cbranch_scc1 .Ls4dr_no
	s_waitcnt vmcnt(4)
	v_readfirstlane_b32 s0, v247
	s_nop 1
	v_add_u32_e32 v74, s0, v74
	v_min_u32_e32 v74, 0x8b7, v74
	v_add_u32_e32 v74, 0xc99, v74
.Ls4dr_no:
	s_xor_b32 s0, s37, 25
	s_lshl_b32 s0, s0, 2
	s_add_i32 s0, s0, 0
	s_add_i32 s0, s0, 0x20140
	v_mov_b32_e32 v2, s0
	ds_write_b32 v2, v74
